# sel branch inner loop hand-rewritten: next-tile QK MFMAs and current-tile PV MFMAs interleaved into the softmax exp stream (2 score register sets), list/selection-mask lookups prefetched; FoX cum-load
# speedup vs baseline: 1.0233x; 1.0233x over previous
.LBB0_783:
	v_readlane_b32 s8, v254, 38
	v_mov_b64_e32 v[4:5], s[0:1]
	s_nop 0
	v_mov_b32_e32 v2, s8
	ds_read_b32 v2, v2
	s_waitcnt lgkmcnt(0)
	v_lshlrev_b32_e32 v3, 6, v2
	v_add_u32_e32 v6, v3, v157
	v_mad_i64_i32 v[4:5], s[8:9], v6, s90, v[4:5]
	v_lshl_add_u64 v[4:5], v[4:5], 0, v[0:1]
	global_load_dwordx4 v[132:135], v[4:5], off offset:1024
	global_load_dwordx4 v[136:139], v[4:5], off offset:2048
	s_and_saveexec_b64 s[8:9], s[6:7]
	s_cbranch_execz .LBB0_785
	v_add_u32_e32 v4, v3, v159
	v_ashrrev_i32_e32 v5, 31, v4
	v_lshl_add_u64 v[4:5], v[4:5], 2, s[4:5]
	global_load_dword v170, v[4:5], off
	v_ashrrev_i32_e32 v2, 3, v2
	v_lshlrev_b32_e32 v2, 2, v2
	v_add_u32_e32 v2, s28, v2
	ds_read_b32 v223, v2

.LBB0_790:
	s_add_i32 s8, s13, -1
	s_cmp_lt_i32 s8, s12
	s_cselect_b64 s[0:1], -1, 0
	s_cmp_ge_i32 s8, s12
	s_cbranch_scc1 .LBB0_794
	v_mov_b32_e32 v0, s19
	ds_read_b32 v0, v0 offset:12
	s_waitcnt lgkmcnt(0)
	v_lshlrev_b32_e32 v2, 6, v0
	v_add_u32_e32 v3, v2, v157
	v_mad_i64_i32 v[52:53], s[8:9], v3, s90, v[168:169]
	global_load_dwordx4 v[140:143], v[52:53], off offset:1024
	global_load_dwordx4 v[144:147], v[52:53], off offset:2048
	s_and_saveexec_b64 s[8:9], s[6:7]
	s_cbranch_execz .LBB0_793
	v_add_u32_e32 v2, v2, v159
	v_ashrrev_i32_e32 v3, 31, v2
	v_lshl_add_u64 v[2:3], v[2:3], 2, s[4:5]
	global_load_dword v167, v[2:3], off
	v_ashrrev_i32_e32 v0, 3, v0
	v_lshlrev_b32_e32 v0, 2, v0
	v_add_u32_e32 v0, s28, v0
	ds_read_b32 v222, v0

.LBB0_798:
	v_exp_f32_e32 v2, v68
	v_exp_f32_e32 v3, v69
	v_exp_f32_e32 v52, v52
	v_exp_f32_e32 v53, v53
	v_exp_f32_e32 v70, v70
	v_exp_f32_e32 v71, v71
	v_exp_f32_e32 v54, v54
	v_exp_f32_e32 v55, v55
	v_pk_add_f32 v[68:69], v[2:3], 0 op_sel_hi:[1,0]
	v_exp_f32_e32 v72, v72
	v_exp_f32_e32 v73, v73
	v_pk_add_f32 v[68:69], v[52:53], v[68:69]
	v_exp_f32_e32 v56, v56
	v_exp_f32_e32 v57, v57
	v_pk_add_f32 v[68:69], v[70:71], v[68:69]
	v_exp_f32_e32 v74, v74
	v_exp_f32_e32 v75, v75
	v_pk_add_f32 v[68:69], v[54:55], v[68:69]
	v_exp_f32_e32 v58, v58
	v_exp_f32_e32 v59, v59
	v_pk_add_f32 v[68:69], v[72:73], v[68:69]
	v_exp_f32_e32 v76, v76
	v_exp_f32_e32 v77, v77
	v_pk_add_f32 v[68:69], v[56:57], v[68:69]
	v_exp_f32_e32 v60, v60
	v_exp_f32_e32 v61, v61
	v_pk_add_f32 v[68:69], v[74:75], v[68:69]
	v_exp_f32_e32 v78, v78
	v_exp_f32_e32 v79, v79
	v_pk_add_f32 v[68:69], v[58:59], v[68:69]
	v_exp_f32_e32 v62, v62
	v_exp_f32_e32 v63, v63
	v_pk_add_f32 v[68:69], v[76:77], v[68:69]
	v_exp_f32_e32 v80, v80
	v_exp_f32_e32 v81, v81
	v_pk_add_f32 v[68:69], v[60:61], v[68:69]
	v_exp_f32_e32 v64, v64
	v_exp_f32_e32 v65, v65
	v_pk_add_f32 v[68:69], v[78:79], v[68:69]
	v_exp_f32_e32 v82, v82
	v_exp_f32_e32 v83, v83
	v_pk_add_f32 v[68:69], v[62:63], v[68:69]
	v_exp_f32_e32 v66, v66
	v_exp_f32_e32 v67, v67
	v_pk_add_f32 v[68:69], v[80:81], v[68:69]
	v_cvt_pk_bf16_f32 v88, v60, v61
	v_pk_add_f32 v[68:69], v[64:65], v[68:69]
	v_cvt_pk_bf16_f32 v89, v62, v63
	v_pk_add_f32 v[68:69], v[82:83], v[68:69]
	s_add_i32 s8, s17, 1
	v_pk_add_f32 v[68:69], v[66:67], v[68:69]
	s_cmp_lg_u32 s8, 3
	v_pk_add_f32 v[84:85], v[68:69], v[68:69] op_sel:[0,1] op_sel_hi:[1,0]
	v_cvt_pk_bf16_f32 v69, v70, v71
	v_cvt_pk_bf16_f32 v70, v72, v73
	v_cvt_pk_bf16_f32 v71, v74, v75
	v_cvt_pk_bf16_f32 v72, v76, v77
	v_cvt_pk_bf16_f32 v73, v78, v79
	v_cvt_pk_bf16_f32 v74, v80, v81
	v_cvt_pk_bf16_f32 v75, v82, v83
	v_cvt_pk_bf16_f32 v76, v52, v53
	v_cvt_pk_bf16_f32 v77, v54, v55
	v_cvt_pk_bf16_f32 v78, v56, v57
	v_cvt_pk_bf16_f32 v79, v58, v59
	ds_read_b128 v[52:55], v0 offset:9216
	ds_read_b128 v[56:59], v0 offset:9248
	ds_read_b128 v[60:63], v0 offset:9280
	ds_read_b128 v[80:83], v0 offset:9312
	s_cselect_b32 s22, s8, 0
	s_add_i32 s8, s22, 1
	s_cmp_lg_u32 s8, 3
	v_mov_b32_e32 v85, v84
	s_cselect_b32 s17, s8, 0
	s_nop 0
	v_permlane32_swap_b32_e32 v84, v85
	v_cvt_pk_bf16_f32 v68, v2, v3
	v_cvt_pk_bf16_f32 v90, v64, v65
	v_cvt_pk_bf16_f32 v91, v66, v67
	s_waitcnt lgkmcnt(3)
	v_mfma_f32_32x32x16_bf16 v[36:51], v[52:55], v[68:71], v[36:51]
	s_waitcnt lgkmcnt(2)
	v_mfma_f32_32x32x16_bf16 v[36:51], v[56:59], v[72:75], v[36:51]
	s_waitcnt lgkmcnt(1)
	v_mfma_f32_32x32x16_bf16 v[36:51], v[60:63], v[76:79], v[36:51]
	s_nop 11
	v_mov_b64_e32 v[66:67], v[50:51]
	v_mov_b64_e32 v[64:65], v[48:49]
	v_mov_b64_e32 v[62:63], v[46:47]
	v_mov_b64_e32 v[60:61], v[44:45]
	v_mov_b64_e32 v[58:59], v[42:43]
	v_mov_b64_e32 v[56:57], v[40:41]
	v_mov_b64_e32 v[54:55], v[38:39]
	v_mov_b64_e32 v[52:53], v[36:37]
	s_waitcnt lgkmcnt(0)
	s_nop 0
	v_mfma_f32_32x32x16_bf16 v[52:67], v[80:83], v[88:91], v[52:67]
	ds_read_b128 v[36:39], v0 offset:13824
	ds_read_b128 v[40:43], v0 offset:13856
	ds_read_b128 v[44:47], v0 offset:13888
	ds_read_b128 v[48:51], v0 offset:13920
	s_waitcnt lgkmcnt(3)
	v_mfma_f32_32x32x16_bf16 v[20:35], v[36:39], v[68:71], v[20:35]
	s_waitcnt lgkmcnt(2)
	v_mfma_f32_32x32x16_bf16 v[20:35], v[40:43], v[72:75], v[20:35]
	s_waitcnt lgkmcnt(1)
	v_mfma_f32_32x32x16_bf16 v[20:35], v[44:47], v[76:79], v[20:35]
	s_nop 11
	v_mov_b64_e32 v[82:83], v[34:35]
	v_mov_b64_e32 v[80:81], v[32:33]
	v_mov_b64_e32 v[78:79], v[30:31]
	v_mov_b64_e32 v[76:77], v[28:29]
	v_mov_b64_e32 v[74:75], v[26:27]
	v_mov_b64_e32 v[72:73], v[24:25]
	v_mov_b64_e32 v[70:71], v[22:23]
	v_mov_b64_e32 v[68:69], v[20:21]
	s_waitcnt lgkmcnt(0)
	s_nop 0
	v_mfma_f32_32x32x16_bf16 v[68:83], v[48:51], v[88:91], v[68:83]
	s_add_i32 s21, s13, -2
	s_cmp_ge_i32 s21, s12
	s_cbranch_scc1 .LBB0_802
	s_mul_i32 s8, s17, 0x4900
	s_add_i32 s10, s33, s8
	v_add3_u32 v0, s10, v171, v166
	s_waitcnt vmcnt(1)
	ds_write_b128 v0, v[132:135]
	s_waitcnt vmcnt(0)
	ds_write_b128 v0, v[136:139] offset:9216
	s_and_saveexec_b64 s[8:9], s[6:7]
	s_cbranch_execz .LBB0_801
	v_add_f32_e32 v170, v170, v223
	v_sub_f32_e32 v170, v155, v170
	v_cvt_pk_bf16_f32 v0, v170, 0
	v_and_b32_e32 v2, 0xffff, v0
	v_lshlrev_b32_e32 v0, 16, v0
	v_sub_f32_e32 v0, v170, v0
	v_cvt_pk_bf16_f32 v0, v0, 0
	v_lshl_or_b32 v0, v0, 16, v2
	v_mov_b32_e32 v2, v1
	v_mov_b32_e32 v3, v1
	v_add_u32_e32 v20, s10, v172
	ds_write_b128 v20, v[0:3] offset:128

.LBB0_802:
	s_waitcnt lgkmcnt(0)
	s_barrier
	v_add_f32_e32 v0, v84, v85
	s_add_i32 s10, s13, -3
	v_add_f32_e32 v175, v86, v0
	s_mov_b64 s[8:9], -1
	s_cmp_ge_i32 s10, s12
	s_mov_b64 s[10:11], -1
	s_cbranch_scc1 .LBB0_789
	s_cmp_ge_i32 s13, s12
	s_cbranch_scc1 .LBB0_807
	v_mov_b32_e32 v0, s19
	ds_read_b32 v0, v0 offset:16
	s_waitcnt lgkmcnt(0)
	v_lshlrev_b32_e32 v2, 6, v0
	v_add_u32_e32 v3, v2, v157
	v_mad_i64_i32 v[20:21], s[8:9], v3, s90, v[168:169]
	global_load_dwordx4 v[132:135], v[20:21], off offset:1024
	global_load_dwordx4 v[136:139], v[20:21], off offset:2048
	s_and_saveexec_b64 s[8:9], s[6:7]
	s_cbranch_execz .LBB0_806
	v_add_u32_e32 v2, v2, v159
	v_ashrrev_i32_e32 v3, 31, v2
	v_lshl_add_u64 v[2:3], v[2:3], 2, s[4:5]
	global_load_dword v170, v[2:3], off
	v_ashrrev_i32_e32 v0, 3, v0
	v_lshlrev_b32_e32 v0, 2, v0
	v_add_u32_e32 v0, s28, v0
	ds_read_b32 v223, v0

.LBB0_812:
	v_exp_f32_e32 v2, v100
	v_exp_f32_e32 v3, v101
	v_exp_f32_e32 v100, v84
	v_exp_f32_e32 v101, v85
	v_exp_f32_e32 v102, v102
	v_exp_f32_e32 v103, v103
	v_exp_f32_e32 v178, v86
	v_exp_f32_e32 v179, v87
	v_pk_add_f32 v[84:85], v[2:3], 0 op_sel_hi:[1,0]
	v_exp_f32_e32 v104, v104
	v_exp_f32_e32 v105, v105
	v_pk_add_f32 v[84:85], v[100:101], v[84:85]
	v_exp_f32_e32 v204, v88
	v_exp_f32_e32 v205, v89
	v_pk_add_f32 v[84:85], v[102:103], v[84:85]
	v_exp_f32_e32 v106, v106
	v_exp_f32_e32 v107, v107
	v_pk_add_f32 v[84:85], v[178:179], v[84:85]
	v_exp_f32_e32 v206, v90
	v_exp_f32_e32 v207, v91
	v_pk_add_f32 v[84:85], v[104:105], v[84:85]
	v_exp_f32_e32 v90, v108
	v_exp_f32_e32 v91, v109
	v_pk_add_f32 v[84:85], v[204:205], v[84:85]
	v_exp_f32_e32 v108, v92
	v_exp_f32_e32 v109, v93
	v_pk_add_f32 v[84:85], v[106:107], v[84:85]
	v_exp_f32_e32 v92, v110
	v_exp_f32_e32 v93, v111
	v_pk_add_f32 v[84:85], v[206:207], v[84:85]
	v_exp_f32_e32 v110, v94
	v_exp_f32_e32 v111, v95
	v_pk_add_f32 v[84:85], v[90:91], v[84:85]
	v_exp_f32_e32 v94, v112
	v_exp_f32_e32 v95, v113
	v_pk_add_f32 v[84:85], v[108:109], v[84:85]
	v_exp_f32_e32 v112, v96
	v_exp_f32_e32 v113, v97
	v_pk_add_f32 v[84:85], v[92:93], v[84:85]
	v_exp_f32_e32 v96, v114
	v_exp_f32_e32 v97, v115
	v_pk_add_f32 v[84:85], v[110:111], v[84:85]
	v_exp_f32_e32 v114, v98
	v_pk_add_f32 v[84:85], v[94:95], v[84:85]
	v_exp_f32_e32 v115, v99
	v_pk_add_f32 v[84:85], v[112:113], v[84:85]
	v_cvt_pk_bf16_f32 v87, v102, v103
	v_pk_add_f32 v[84:85], v[96:97], v[84:85]
	v_cvt_pk_bf16_f32 v88, v104, v105
	v_cvt_pk_bf16_f32 v89, v106, v107
	v_cvt_pk_bf16_f32 v90, v90, v91
	v_cvt_pk_bf16_f32 v91, v92, v93
	v_cvt_pk_bf16_f32 v92, v94, v95
	v_cvt_pk_bf16_f32 v93, v96, v97
	v_cvt_pk_bf16_f32 v94, v100, v101
	v_cvt_pk_bf16_f32 v96, v204, v205
	v_cvt_pk_bf16_f32 v97, v206, v207
	v_cvt_pk_bf16_f32 v98, v108, v109
	v_cvt_pk_bf16_f32 v99, v110, v111
	v_cvt_pk_bf16_f32 v100, v112, v113
	ds_read_b128 v[102:105], v0 offset:9216
	ds_read_b128 v[106:109], v0 offset:9248
	ds_read_b128 v[110:113], v0 offset:9280
	ds_read_b128 v[204:207], v0 offset:9312
	v_pk_add_f32 v[84:85], v[114:115], v[84:85]
	v_cvt_pk_bf16_f32 v86, v2, v3
	v_pk_add_f32 v[84:85], v[84:85], v[84:85] op_sel:[0,1] op_sel_hi:[1,0]
	v_cvt_pk_bf16_f32 v95, v178, v179
	v_mov_b32_e32 v85, v84
	s_nop 1
	v_permlane32_swap_b32_e32 v84, v85
	v_cvt_pk_bf16_f32 v101, v114, v115
	s_waitcnt lgkmcnt(3)
	v_mfma_f32_32x32x16_bf16 v[36:51], v[102:105], v[86:89], v[36:51]
	s_waitcnt lgkmcnt(2)
	v_mfma_f32_32x32x16_bf16 v[36:51], v[106:109], v[90:93], v[36:51]
	s_waitcnt lgkmcnt(1)
	v_mfma_f32_32x32x16_bf16 v[36:51], v[110:113], v[94:97], v[36:51]
	s_waitcnt lgkmcnt(0)
	v_mfma_f32_32x32x16_bf16 v[36:51], v[204:207], v[98:101], v[36:51]
	ds_read_b128 v[102:105], v0 offset:13824
	ds_read_b128 v[106:109], v0 offset:13856
	ds_read_b128 v[110:113], v0 offset:13888
	ds_read_b128 v[204:207], v0 offset:13920
	s_waitcnt lgkmcnt(3)
	v_mfma_f32_32x32x16_bf16 v[20:35], v[102:105], v[86:89], v[20:35]
	s_waitcnt lgkmcnt(2)
	v_mfma_f32_32x32x16_bf16 v[20:35], v[106:109], v[90:93], v[20:35]
	s_waitcnt lgkmcnt(1)
	v_mfma_f32_32x32x16_bf16 v[20:35], v[110:113], v[94:97], v[20:35]
	s_waitcnt lgkmcnt(0)
	v_mfma_f32_32x32x16_bf16 v[20:35], v[204:207], v[98:101], v[20:35]
	s_andn2_b64 vcc, exec, s[0:1]
	s_cbranch_vccnz .LBB0_788
	v_add3_u32 v0, s20, v171, v166
	s_waitcnt vmcnt(1)
	ds_write_b128 v0, v[140:143]
	s_waitcnt vmcnt(0)
	ds_write_b128 v0, v[144:147] offset:9216
	s_and_saveexec_b64 s[0:1], s[6:7]
	s_cbranch_execz .LBB0_787
	v_add_f32_e32 v167, v167, v222
	v_sub_f32_e32 v167, v155, v167
	v_cvt_pk_bf16_f32 v0, v167, 0
	v_and_b32_e32 v2, 0xffff, v0
	v_lshlrev_b32_e32 v0, 16, v0
	v_sub_f32_e32 v0, v167, v0
	v_cvt_pk_bf16_f32 v0, v0, 0
	v_lshl_or_b32 v0, v0, 16, v2
	v_mov_b32_e32 v2, v1
	v_mov_b32_e32 v3, v1
	v_add_u32_e32 v86, s20, v172
	ds_write_b128 v86, v[0:3] offset:128
	s_branch .LBB0_787

.Lsel_pre:
	s_mov_b32 s76, 0
	s_mov_b32 s81, 0
	s_movk_i32 s82, 0x4900
	s_mov_b32 s83, 0x9200
	v_mov_b32_e32 v0, s77
	ds_read_b32 v107, v0
	ds_read_b32 v160, v0 offset:4
	ds_read_b32 v184, v0 offset:8
	ds_read_b32 v182, v0 offset:12
	s_waitcnt lgkmcnt(0)
	v_readfirstlane_b32 s1, v107
	v_readfirstlane_b32 s0, v160
	v_readfirstlane_b32 s86, v184
	s_nop 1
	s_lshr_b32 s98, s1, 5
	s_and_b32 s98, s98, 3
	s_lshl_b32 s98, s98, 2
	v_add_u32_e32 v107, s98, v103
	ds_read_b32 v107, v107
	s_lshr_b32 s98, s0, 5
	s_and_b32 s98, s98, 3
	s_lshl_b32 s98, s98, 2
	v_add_u32_e32 v160, s98, v103
	ds_read_b32 v160, v160
	s_waitcnt lgkmcnt(0)
	s_and_b32 s98, s1, 31
	v_bfe_u32 v107, v107, s98, 1
	v_cmp_eq_u32_e64 s[72:73], 0, v107
	s_and_b32 s98, s0, 31
	v_bfe_u32 v160, v160, s98, 1
	v_cmp_eq_u32_e64 s[100:101], 0, v160
	s_cmp_ge_u32 s79, 2
	s_cbranch_scc1 .Lsel_pre_n1
	s_mov_b64 s[100:101], -1
.Lsel_pre_n1:
	s_nop 1
	s_cmp_lg_u64 s[72:73], -1
	s_cbranch_scc0 .Lsel_step_0
	v_add_u32_e32 v0, s81, v208
	ds_read_b128 v[108:111], v0
	ds_read_b128 v[112:115], v0 offset:4608
	ds_read_b128 v[116:119], v0 offset:32
	ds_read_b128 v[120:123], v0 offset:4640
	s_waitcnt lgkmcnt(3)
	v_mfma_f32_32x32x16_bf16 v[80:95], v[108:111], v[128:131], v[2:17]
	ds_read_b128 v[108:111], v0 offset:64
	s_waitcnt lgkmcnt(3)
	v_mfma_f32_32x32x16_bf16 v[64:79], v[112:115], v[128:131], v[2:17]
	ds_read_b128 v[112:115], v0 offset:4672
	s_waitcnt lgkmcnt(3)
	v_mfma_f32_32x32x16_bf16 v[80:95], v[116:119], v[132:135], v[80:95]
	ds_read_b128 v[116:119], v0 offset:96
	s_waitcnt lgkmcnt(3)
	v_mfma_f32_32x32x16_bf16 v[64:79], v[120:123], v[132:135], v[64:79]
	ds_read_b128 v[120:123], v0 offset:4704
	s_waitcnt lgkmcnt(3)
	v_mfma_f32_32x32x16_bf16 v[80:95], v[108:111], v[136:139], v[80:95]
	s_waitcnt lgkmcnt(2)
	v_mfma_f32_32x32x16_bf16 v[64:79], v[112:115], v[136:139], v[64:79]
	s_waitcnt lgkmcnt(1)
	v_mfma_f32_32x32x16_bf16 v[80:95], v[116:119], v[140:143], v[80:95]
	s_waitcnt lgkmcnt(0)
	v_mfma_f32_32x32x16_bf16 v[64:79], v[120:123], v[140:143], v[64:79]
.Lsel_step_0:
	s_add_u32 s1, s76, 3
	s_cmp_lt_u32 s1, s79
	s_cbranch_scc0 .Lsel_nogl_0
	v_lshl_add_u32 v0, v182, 6, v100
	v_mad_i64_i32 v[18:19], vcc, v0, s90, v[30:31]
	v_mad_i64_i32 v[22:23], vcc, v0, s90, v[104:105]
	global_load_dwordx4 v[18:21], v[18:19], off
	s_nop 0
	global_load_dwordx4 v[22:25], v[22:23], off
.Lsel_nogl_0:
	v_readfirstlane_b32 s0, v182
	s_lshr_b32 s98, s86, 5
	s_and_b32 s98, s98, 3
	s_lshl_b32 s98, s98, 2
	v_add_u32_e32 v184, s98, v103
	ds_read_b32 v184, v184
	s_cmp_lg_u64 s[100:101], -1
	s_cbranch_scc0 .Lsel_noN_0
	s_cmp_lg_u64 s[72:73], -1
	s_cbranch_scc0 .Lsel_Nonly_0
	v_add_u32_e32 v0, s82, v208
	ds_read_b128 v[108:111], v0
	ds_read_b128 v[112:115], v0 offset:4608
	ds_read_b128 v[116:119], v0 offset:32
	ds_read_b128 v[120:123], v0 offset:4640
	s_add_u32 s1, s76, 1
	s_cmp_lg_u32 s1, s79
	s_cbranch_scc1 .Lsel_nodiag_0b
	v_cndmask_b32_e64 v80, v80, v185, s[6:7]
	v_cndmask_b32_e64 v64, v64, v185, s[8:9]
	v_cndmask_b32_e64 v81, v185, v81, s[10:11]
	v_cndmask_b32_e64 v65, v65, v185, s[12:13]
	v_cndmask_b32_e64 v82, v82, v185, s[14:15]
	v_cndmask_b32_e64 v66, v66, v185, s[16:17]
	v_cndmask_b32_e64 v83, v83, v185, s[18:19]
	v_cndmask_b32_e64 v67, v67, v185, s[20:21]
	v_cndmask_b32_e64 v84, v84, v185, s[22:23]
	v_cndmask_b32_e64 v68, v68, v185, s[24:25]
	v_cndmask_b32_e64 v85, v85, v185, s[26:27]
	v_cndmask_b32_e64 v69, v69, v185, s[28:29]
	v_cndmask_b32_e64 v86, v86, v185, s[30:31]
	v_cndmask_b32_e64 v70, v70, v185, s[34:35]
	v_cndmask_b32_e64 v87, v87, v185, s[36:37]
	v_cndmask_b32_e64 v71, v71, v185, s[38:39]
	v_cndmask_b32_e64 v88, v88, v185, s[40:41]
	v_cndmask_b32_e64 v72, v72, v185, s[42:43]
	v_cndmask_b32_e64 v89, v89, v185, s[44:45]
	v_cndmask_b32_e64 v73, v73, v185, s[46:47]
	v_cndmask_b32_e64 v90, v90, v185, s[48:49]
	v_cndmask_b32_e64 v74, v74, v185, s[50:51]
	v_cndmask_b32_e64 v91, v91, v185, s[52:53]
	v_cndmask_b32_e64 v75, v75, v185, s[54:55]
	v_cndmask_b32_e64 v92, v92, v185, s[56:57]
	v_cndmask_b32_e64 v76, v76, v185, s[58:59]
	v_cndmask_b32_e64 v93, v93, v185, s[60:61]
	v_cndmask_b32_e64 v77, v77, v185, s[62:63]
	v_cndmask_b32_e64 v94, v94, v185, s[64:65]
	v_cndmask_b32_e64 v78, v78, v185, s[66:67]
	v_cndmask_b32_e64 v95, v95, v185, s[68:69]
	v_cndmask_b32_e64 v79, v79, v185, s[70:71]
.Lsel_nodiag_0b:
	v_max3_f32 v107, v80, v81, v82
	v_max3_f32 v160, v64, v65, v66
	v_max3_f32 v107, v107, v83, v84
	v_max3_f32 v160, v160, v67, v68
	v_max3_f32 v107, v107, v85, v86
	v_max3_f32 v160, v160, v69, v70
	v_max3_f32 v107, v107, v87, v88
	v_max3_f32 v160, v160, v71, v72
	v_max3_f32 v107, v107, v89, v90
	v_max3_f32 v160, v160, v73, v74
	v_max3_f32 v107, v107, v91, v92
	v_max3_f32 v160, v160, v75, v76
	v_max_f32_e32 v162, v79, v79
	v_max_f32_e32 v163, v95, v95
	v_max3_f32 v107, v107, v93, v94
	v_max3_f32 v160, v160, v77, v78
	v_max_f32_e32 v162, v163, v162
	v_max3_f32 v107, v107, v160, v162
	v_mov_b32_e32 v160, v107
	s_nop 1
	v_permlane32_swap_b32_e32 v107, v160
	v_max_f32_e32 v160, v160, v160
	v_max_f32_e32 v107, v107, v107
	v_max_f32_e32 v107, v107, v160
	v_cndmask_b32_e64 v107, v107, v185, s[72:73]
	v_cmp_lt_f32_e32 vcc, s91, v107
	s_cbranch_vccz .Lsel_noresc_0b
	s_nop 15
	s_nop 15
	v_max_f32_e32 v107, v107, v107
	v_max_f32_e32 v160, 0, v107
	v_exp_f32_e64 v162, -v160
	v_pk_add_f32 v[80:81], v[80:81], v[160:161] op_sel_hi:[1,0] neg_lo:[0,1] neg_hi:[0,1]
	v_pk_add_f32 v[64:65], v[64:65], v[160:161] op_sel_hi:[1,0] neg_lo:[0,1] neg_hi:[0,1]
	v_pk_add_f32 v[82:83], v[82:83], v[160:161] op_sel_hi:[1,0] neg_lo:[0,1] neg_hi:[0,1]
	v_pk_add_f32 v[66:67], v[66:67], v[160:161] op_sel_hi:[1,0] neg_lo:[0,1] neg_hi:[0,1]
	v_pk_add_f32 v[84:85], v[84:85], v[160:161] op_sel_hi:[1,0] neg_lo:[0,1] neg_hi:[0,1]
	v_pk_add_f32 v[68:69], v[68:69], v[160:161] op_sel_hi:[1,0] neg_lo:[0,1] neg_hi:[0,1]
	v_pk_add_f32 v[86:87], v[86:87], v[160:161] op_sel_hi:[1,0] neg_lo:[0,1] neg_hi:[0,1]
	v_pk_add_f32 v[70:71], v[70:71], v[160:161] op_sel_hi:[1,0] neg_lo:[0,1] neg_hi:[0,1]
	v_pk_add_f32 v[88:89], v[88:89], v[160:161] op_sel_hi:[1,0] neg_lo:[0,1] neg_hi:[0,1]
	v_pk_add_f32 v[72:73], v[72:73], v[160:161] op_sel_hi:[1,0] neg_lo:[0,1] neg_hi:[0,1]
	v_pk_add_f32 v[90:91], v[90:91], v[160:161] op_sel_hi:[1,0] neg_lo:[0,1] neg_hi:[0,1]
	v_pk_add_f32 v[74:75], v[74:75], v[160:161] op_sel_hi:[1,0] neg_lo:[0,1] neg_hi:[0,1]
	v_pk_add_f32 v[92:93], v[92:93], v[160:161] op_sel_hi:[1,0] neg_lo:[0,1] neg_hi:[0,1]
	v_pk_add_f32 v[76:77], v[76:77], v[160:161] op_sel_hi:[1,0] neg_lo:[0,1] neg_hi:[0,1]
	v_pk_add_f32 v[94:95], v[94:95], v[160:161] op_sel_hi:[1,0] neg_lo:[0,1] neg_hi:[0,1]
	v_pk_add_f32 v[78:79], v[78:79], v[160:161] op_sel_hi:[1,0] neg_lo:[0,1] neg_hi:[0,1]
	v_mul_f32_e32 v106, v106, v162
	v_sub_f32_e32 v2, v2, v160
	v_sub_f32_e32 v3, v3, v160
	v_sub_f32_e32 v4, v4, v160
	v_sub_f32_e32 v5, v5, v160
	v_sub_f32_e32 v6, v6, v160
	v_sub_f32_e32 v7, v7, v160
	v_sub_f32_e32 v8, v8, v160
	v_sub_f32_e32 v9, v9, v160
	v_sub_f32_e32 v10, v10, v160
	v_sub_f32_e32 v11, v11, v160
	v_sub_f32_e32 v12, v12, v160
	v_sub_f32_e32 v13, v13, v160
	v_sub_f32_e32 v14, v14, v160
	v_sub_f32_e32 v15, v15, v160
	v_sub_f32_e32 v16, v16, v160
	v_sub_f32_e32 v17, v17, v160
	v_pk_mul_f32 v[48:49], v[48:49], v[162:163] op_sel_hi:[1,0]
	v_pk_mul_f32 v[32:33], v[32:33], v[162:163] op_sel_hi:[1,0]
	v_pk_mul_f32 v[50:51], v[50:51], v[162:163] op_sel_hi:[1,0]
	v_pk_mul_f32 v[34:35], v[34:35], v[162:163] op_sel_hi:[1,0]
	v_pk_mul_f32 v[52:53], v[52:53], v[162:163] op_sel_hi:[1,0]
	v_pk_mul_f32 v[36:37], v[36:37], v[162:163] op_sel_hi:[1,0]
	v_pk_mul_f32 v[54:55], v[54:55], v[162:163] op_sel_hi:[1,0]
	v_pk_mul_f32 v[38:39], v[38:39], v[162:163] op_sel_hi:[1,0]
	v_pk_mul_f32 v[56:57], v[56:57], v[162:163] op_sel_hi:[1,0]
	v_pk_mul_f32 v[40:41], v[40:41], v[162:163] op_sel_hi:[1,0]
	v_pk_mul_f32 v[58:59], v[58:59], v[162:163] op_sel_hi:[1,0]
	v_pk_mul_f32 v[42:43], v[42:43], v[162:163] op_sel_hi:[1,0]
	v_pk_mul_f32 v[60:61], v[60:61], v[162:163] op_sel_hi:[1,0]
	v_pk_mul_f32 v[44:45], v[44:45], v[162:163] op_sel_hi:[1,0]
	v_pk_mul_f32 v[62:63], v[62:63], v[162:163] op_sel_hi:[1,0]
	v_pk_mul_f32 v[46:47], v[46:47], v[162:163] op_sel_hi:[1,0]
	s_nop 1
.Lsel_noresc_0b:
	v_add_u32_e32 v187, s81, v208
	ds_read_b128 v[124:127], v187 offset:9216
	ds_read_b128 v[144:147], v187 offset:13824
	ds_read_b128 v[148:151], v187 offset:9248
	v_exp_f32_e32 v80, v80
	v_exp_f32_e32 v81, v81
	v_exp_f32_e32 v82, v82
	v_exp_f32_e32 v83, v83
	s_waitcnt lgkmcnt(6)
	v_mfma_f32_32x32x16_bf16 v[238:253], v[108:111], v[128:131], v[2:17]
	ds_read_b128 v[108:111], v0 offset:64
	v_exp_f32_e32 v84, v84
	v_exp_f32_e32 v85, v85
	v_exp_f32_e32 v86, v86
	v_exp_f32_e32 v87, v87
	s_waitcnt lgkmcnt(6)
	v_mfma_f32_32x32x16_bf16 v[222:237], v[112:115], v[128:131], v[2:17]
	ds_read_b128 v[112:115], v0 offset:4672
	v_pk_add_f32 v[164:165], v[80:81], 0 op_sel_hi:[1,0]
	v_pk_add_f32 v[164:165], v[82:83], v[164:165]
	v_cvt_pk_bf16_f32 v80, v80, v81
	v_cvt_pk_bf16_f32 v81, v82, v83
	v_pk_add_f32 v[164:165], v[84:85], v[164:165]
	v_pk_add_f32 v[164:165], v[86:87], v[164:165]
	v_cvt_pk_bf16_f32 v82, v84, v85
	v_cvt_pk_bf16_f32 v83, v86, v87
	v_cndmask_b32_e64 v80, v80, 0, s[72:73]
	v_cndmask_b32_e64 v81, v81, 0, s[72:73]
	v_cndmask_b32_e64 v82, v82, 0, s[72:73]
	v_cndmask_b32_e64 v83, v83, 0, s[72:73]
	v_exp_f32_e32 v88, v88
	v_exp_f32_e32 v89, v89
	s_waitcnt lgkmcnt(4)
	v_mfma_f32_32x32x16_bf16 v[48:63], v[124:127], v[80:83], v[48:63]
	ds_read_b128 v[124:127], v187 offset:13856
	v_exp_f32_e32 v90, v90
	v_exp_f32_e32 v91, v91
	s_waitcnt lgkmcnt(4)
	v_mfma_f32_32x32x16_bf16 v[32:47], v[144:147], v[80:83], v[32:47]
	ds_read_b128 v[144:147], v187 offset:9280
	v_exp_f32_e32 v92, v92
	v_exp_f32_e32 v93, v93
	v_mfma_f32_32x32x16_bf16 v[238:253], v[116:119], v[132:135], v[238:253]
	ds_read_b128 v[116:119], v0 offset:96
	v_exp_f32_e32 v94, v94
	v_exp_f32_e32 v95, v95
	v_mfma_f32_32x32x16_bf16 v[222:237], v[120:123], v[132:135], v[222:237]
	ds_read_b128 v[120:123], v0 offset:4704
	v_pk_add_f32 v[164:165], v[88:89], v[164:165]
	v_pk_add_f32 v[164:165], v[90:91], v[164:165]
	v_cvt_pk_bf16_f32 v88, v88, v89
	v_cvt_pk_bf16_f32 v89, v90, v91
	v_pk_add_f32 v[164:165], v[92:93], v[164:165]
	v_pk_add_f32 v[164:165], v[94:95], v[164:165]
	v_cvt_pk_bf16_f32 v90, v92, v93
	v_cvt_pk_bf16_f32 v91, v94, v95
	v_cndmask_b32_e64 v88, v88, 0, s[72:73]
	v_cndmask_b32_e64 v89, v89, 0, s[72:73]
	v_cndmask_b32_e64 v90, v90, 0, s[72:73]
	v_cndmask_b32_e64 v91, v91, 0, s[72:73]
	v_exp_f32_e32 v64, v64
	v_exp_f32_e32 v65, v65
	s_waitcnt lgkmcnt(6)
	v_mfma_f32_32x32x16_bf16 v[48:63], v[148:151], v[88:91], v[48:63]
	ds_read_b128 v[148:151], v187 offset:13888
	v_exp_f32_e32 v66, v66
	v_exp_f32_e32 v67, v67
	s_waitcnt lgkmcnt(4)
	v_mfma_f32_32x32x16_bf16 v[32:47], v[124:127], v[88:91], v[32:47]
	ds_read_b128 v[124:127], v187 offset:9312
	v_exp_f32_e32 v68, v68
	v_exp_f32_e32 v69, v69
	v_mfma_f32_32x32x16_bf16 v[238:253], v[108:111], v[136:139], v[238:253]
	v_exp_f32_e32 v70, v70
	v_exp_f32_e32 v71, v71
	v_mfma_f32_32x32x16_bf16 v[222:237], v[112:115], v[136:139], v[222:237]
	v_pk_add_f32 v[164:165], v[64:65], v[164:165]
	v_pk_add_f32 v[164:165], v[66:67], v[164:165]
	v_cvt_pk_bf16_f32 v64, v64, v65
	v_cvt_pk_bf16_f32 v65, v66, v67
	v_pk_add_f32 v[164:165], v[68:69], v[164:165]
	v_pk_add_f32 v[164:165], v[70:71], v[164:165]
	v_cvt_pk_bf16_f32 v66, v68, v69
	v_cvt_pk_bf16_f32 v67, v70, v71
	v_cndmask_b32_e64 v64, v64, 0, s[72:73]
	v_cndmask_b32_e64 v65, v65, 0, s[72:73]
	v_cndmask_b32_e64 v66, v66, 0, s[72:73]
	v_cndmask_b32_e64 v67, v67, 0, s[72:73]
	v_exp_f32_e32 v72, v72
	v_exp_f32_e32 v73, v73
	s_waitcnt lgkmcnt(4)
	v_mfma_f32_32x32x16_bf16 v[48:63], v[144:147], v[64:67], v[48:63]
	ds_read_b128 v[144:147], v187 offset:13920
	v_exp_f32_e32 v74, v74
	v_exp_f32_e32 v75, v75
	s_waitcnt lgkmcnt(2)
	v_mfma_f32_32x32x16_bf16 v[32:47], v[148:151], v[64:67], v[32:47]
	v_exp_f32_e32 v76, v76
	v_exp_f32_e32 v77, v77
	v_mfma_f32_32x32x16_bf16 v[238:253], v[116:119], v[140:143], v[238:253]
	v_exp_f32_e32 v78, v78
	v_exp_f32_e32 v79, v79
	v_mfma_f32_32x32x16_bf16 v[222:237], v[120:123], v[140:143], v[222:237]
	v_pk_add_f32 v[164:165], v[72:73], v[164:165]
	v_pk_add_f32 v[164:165], v[74:75], v[164:165]
	v_cvt_pk_bf16_f32 v72, v72, v73
	v_cvt_pk_bf16_f32 v73, v74, v75
	v_pk_add_f32 v[164:165], v[76:77], v[164:165]
	v_pk_add_f32 v[164:165], v[78:79], v[164:165]
	v_cvt_pk_bf16_f32 v74, v76, v77
	v_cvt_pk_bf16_f32 v75, v78, v79
	v_cndmask_b32_e64 v72, v72, 0, s[72:73]
	v_cndmask_b32_e64 v73, v73, 0, s[72:73]
	v_cndmask_b32_e64 v74, v74, 0, s[72:73]
	v_cndmask_b32_e64 v75, v75, 0, s[72:73]
	s_nop 1
	s_waitcnt lgkmcnt(1)
	v_mfma_f32_32x32x16_bf16 v[48:63], v[124:127], v[72:75], v[48:63]
	s_waitcnt lgkmcnt(0)
	v_mfma_f32_32x32x16_bf16 v[32:47], v[144:147], v[72:75], v[32:47]
	v_add_f32_e32 v164, v164, v165
	v_cndmask_b32_e64 v164, v164, 0, s[72:73]
	v_add_f32_e32 v106, v106, v164
	s_branch .Lsel_tail_0
.Lsel_Nonly_0:
	v_add_u32_e32 v0, s82, v208
	ds_read_b128 v[108:111], v0
	ds_read_b128 v[112:115], v0 offset:4608
	ds_read_b128 v[116:119], v0 offset:32
	ds_read_b128 v[120:123], v0 offset:4640
	s_waitcnt lgkmcnt(3)
	v_mfma_f32_32x32x16_bf16 v[238:253], v[108:111], v[128:131], v[2:17]
	ds_read_b128 v[108:111], v0 offset:64
	s_waitcnt lgkmcnt(3)
	v_mfma_f32_32x32x16_bf16 v[222:237], v[112:115], v[128:131], v[2:17]
	ds_read_b128 v[112:115], v0 offset:4672
	s_waitcnt lgkmcnt(3)
	v_mfma_f32_32x32x16_bf16 v[238:253], v[116:119], v[132:135], v[238:253]
	ds_read_b128 v[116:119], v0 offset:96
	s_waitcnt lgkmcnt(3)
	v_mfma_f32_32x32x16_bf16 v[222:237], v[120:123], v[132:135], v[222:237]
	ds_read_b128 v[120:123], v0 offset:4704
	s_waitcnt lgkmcnt(3)
	v_mfma_f32_32x32x16_bf16 v[238:253], v[108:111], v[136:139], v[238:253]
	s_waitcnt lgkmcnt(2)
	v_mfma_f32_32x32x16_bf16 v[222:237], v[112:115], v[136:139], v[222:237]
	s_waitcnt lgkmcnt(1)
	v_mfma_f32_32x32x16_bf16 v[238:253], v[116:119], v[140:143], v[238:253]
	s_waitcnt lgkmcnt(0)
	v_mfma_f32_32x32x16_bf16 v[222:237], v[120:123], v[140:143], v[222:237]
	s_branch .Lsel_tail_0
.Lsel_noN_0:
	s_cmp_lg_u64 s[72:73], -1
	s_cbranch_scc0 .Lsel_tail_0
	s_add_u32 s1, s76, 1
	s_cmp_lg_u32 s1, s79
	s_cbranch_scc1 .Lsel_nodiag_0c
	v_cndmask_b32_e64 v80, v80, v185, s[6:7]
	v_cndmask_b32_e64 v64, v64, v185, s[8:9]
	v_cndmask_b32_e64 v81, v185, v81, s[10:11]
	v_cndmask_b32_e64 v65, v65, v185, s[12:13]
	v_cndmask_b32_e64 v82, v82, v185, s[14:15]
	v_cndmask_b32_e64 v66, v66, v185, s[16:17]
	v_cndmask_b32_e64 v83, v83, v185, s[18:19]
	v_cndmask_b32_e64 v67, v67, v185, s[20:21]
	v_cndmask_b32_e64 v84, v84, v185, s[22:23]
	v_cndmask_b32_e64 v68, v68, v185, s[24:25]
	v_cndmask_b32_e64 v85, v85, v185, s[26:27]
	v_cndmask_b32_e64 v69, v69, v185, s[28:29]
	v_cndmask_b32_e64 v86, v86, v185, s[30:31]
	v_cndmask_b32_e64 v70, v70, v185, s[34:35]
	v_cndmask_b32_e64 v87, v87, v185, s[36:37]
	v_cndmask_b32_e64 v71, v71, v185, s[38:39]
	v_cndmask_b32_e64 v88, v88, v185, s[40:41]
	v_cndmask_b32_e64 v72, v72, v185, s[42:43]
	v_cndmask_b32_e64 v89, v89, v185, s[44:45]
	v_cndmask_b32_e64 v73, v73, v185, s[46:47]
	v_cndmask_b32_e64 v90, v90, v185, s[48:49]
	v_cndmask_b32_e64 v74, v74, v185, s[50:51]
	v_cndmask_b32_e64 v91, v91, v185, s[52:53]
	v_cndmask_b32_e64 v75, v75, v185, s[54:55]
	v_cndmask_b32_e64 v92, v92, v185, s[56:57]
	v_cndmask_b32_e64 v76, v76, v185, s[58:59]
	v_cndmask_b32_e64 v93, v93, v185, s[60:61]
	v_cndmask_b32_e64 v77, v77, v185, s[62:63]
	v_cndmask_b32_e64 v94, v94, v185, s[64:65]
	v_cndmask_b32_e64 v78, v78, v185, s[66:67]
	v_cndmask_b32_e64 v95, v95, v185, s[68:69]
	v_cndmask_b32_e64 v79, v79, v185, s[70:71]

.Lsel_noresc_0c:
	v_add_u32_e32 v187, s81, v208
	ds_read_b128 v[124:127], v187 offset:9216
	ds_read_b128 v[144:147], v187 offset:13824
	ds_read_b128 v[148:151], v187 offset:9248
	v_exp_f32_e32 v80, v80
	v_exp_f32_e32 v81, v81
	v_exp_f32_e32 v82, v82
	v_exp_f32_e32 v83, v83
	v_exp_f32_e32 v84, v84
	v_exp_f32_e32 v85, v85
	v_exp_f32_e32 v86, v86
	v_exp_f32_e32 v87, v87
	v_pk_add_f32 v[164:165], v[80:81], 0 op_sel_hi:[1,0]
	v_pk_add_f32 v[164:165], v[82:83], v[164:165]
	v_cvt_pk_bf16_f32 v80, v80, v81
	v_cvt_pk_bf16_f32 v81, v82, v83
	v_pk_add_f32 v[164:165], v[84:85], v[164:165]
	v_pk_add_f32 v[164:165], v[86:87], v[164:165]
	v_cvt_pk_bf16_f32 v82, v84, v85
	v_cvt_pk_bf16_f32 v83, v86, v87
	v_cndmask_b32_e64 v80, v80, 0, s[72:73]
	v_cndmask_b32_e64 v81, v81, 0, s[72:73]
	v_cndmask_b32_e64 v82, v82, 0, s[72:73]
	v_cndmask_b32_e64 v83, v83, 0, s[72:73]
	v_exp_f32_e32 v88, v88
	v_exp_f32_e32 v89, v89
	s_waitcnt lgkmcnt(2)
	v_mfma_f32_32x32x16_bf16 v[48:63], v[124:127], v[80:83], v[48:63]
	ds_read_b128 v[124:127], v187 offset:13856
	v_exp_f32_e32 v90, v90
	v_exp_f32_e32 v91, v91
	s_waitcnt lgkmcnt(2)
	v_mfma_f32_32x32x16_bf16 v[32:47], v[144:147], v[80:83], v[32:47]
	ds_read_b128 v[144:147], v187 offset:9280
	v_exp_f32_e32 v92, v92
	v_exp_f32_e32 v93, v93
	v_exp_f32_e32 v94, v94
	v_exp_f32_e32 v95, v95
	v_pk_add_f32 v[164:165], v[88:89], v[164:165]
	v_pk_add_f32 v[164:165], v[90:91], v[164:165]
	v_cvt_pk_bf16_f32 v88, v88, v89
	v_cvt_pk_bf16_f32 v89, v90, v91
	v_pk_add_f32 v[164:165], v[92:93], v[164:165]
	v_pk_add_f32 v[164:165], v[94:95], v[164:165]
	v_cvt_pk_bf16_f32 v90, v92, v93
	v_cvt_pk_bf16_f32 v91, v94, v95
	v_cndmask_b32_e64 v88, v88, 0, s[72:73]
	v_cndmask_b32_e64 v89, v89, 0, s[72:73]
	v_cndmask_b32_e64 v90, v90, 0, s[72:73]
	v_cndmask_b32_e64 v91, v91, 0, s[72:73]
	v_exp_f32_e32 v64, v64
	v_exp_f32_e32 v65, v65
	s_waitcnt lgkmcnt(2)
	v_mfma_f32_32x32x16_bf16 v[48:63], v[148:151], v[88:91], v[48:63]
	ds_read_b128 v[148:151], v187 offset:13888
	v_exp_f32_e32 v66, v66
	v_exp_f32_e32 v67, v67
	s_waitcnt lgkmcnt(2)
	v_mfma_f32_32x32x16_bf16 v[32:47], v[124:127], v[88:91], v[32:47]
	ds_read_b128 v[124:127], v187 offset:9312
	v_exp_f32_e32 v68, v68
	v_exp_f32_e32 v69, v69
	v_exp_f32_e32 v70, v70
	v_exp_f32_e32 v71, v71
	v_pk_add_f32 v[164:165], v[64:65], v[164:165]
	v_pk_add_f32 v[164:165], v[66:67], v[164:165]
	v_cvt_pk_bf16_f32 v64, v64, v65
	v_cvt_pk_bf16_f32 v65, v66, v67
	v_pk_add_f32 v[164:165], v[68:69], v[164:165]
	v_pk_add_f32 v[164:165], v[70:71], v[164:165]
	v_cvt_pk_bf16_f32 v66, v68, v69
	v_cvt_pk_bf16_f32 v67, v70, v71
	v_cndmask_b32_e64 v64, v64, 0, s[72:73]
	v_cndmask_b32_e64 v65, v65, 0, s[72:73]
	v_cndmask_b32_e64 v66, v66, 0, s[72:73]
	v_cndmask_b32_e64 v67, v67, 0, s[72:73]
	v_exp_f32_e32 v72, v72
	v_exp_f32_e32 v73, v73
	s_waitcnt lgkmcnt(2)
	v_mfma_f32_32x32x16_bf16 v[48:63], v[144:147], v[64:67], v[48:63]
	ds_read_b128 v[144:147], v187 offset:13920
	v_exp_f32_e32 v74, v74
	v_exp_f32_e32 v75, v75
	s_waitcnt lgkmcnt(2)
	v_mfma_f32_32x32x16_bf16 v[32:47], v[148:151], v[64:67], v[32:47]
	v_exp_f32_e32 v76, v76
	v_exp_f32_e32 v77, v77
	v_exp_f32_e32 v78, v78
	v_exp_f32_e32 v79, v79
	v_pk_add_f32 v[164:165], v[72:73], v[164:165]
	v_pk_add_f32 v[164:165], v[74:75], v[164:165]
	v_cvt_pk_bf16_f32 v72, v72, v73
	v_cvt_pk_bf16_f32 v73, v74, v75
	v_pk_add_f32 v[164:165], v[76:77], v[164:165]
	v_pk_add_f32 v[164:165], v[78:79], v[164:165]
	v_cvt_pk_bf16_f32 v74, v76, v77
	v_cvt_pk_bf16_f32 v75, v78, v79
	v_cndmask_b32_e64 v72, v72, 0, s[72:73]
	v_cndmask_b32_e64 v73, v73, 0, s[72:73]
	v_cndmask_b32_e64 v74, v74, 0, s[72:73]
	v_cndmask_b32_e64 v75, v75, 0, s[72:73]
	s_nop 1
	s_waitcnt lgkmcnt(1)
	v_mfma_f32_32x32x16_bf16 v[48:63], v[124:127], v[72:75], v[48:63]
	s_waitcnt lgkmcnt(0)
	v_mfma_f32_32x32x16_bf16 v[32:47], v[144:147], v[72:75], v[32:47]
	v_add_f32_e32 v164, v164, v165
	v_cndmask_b32_e64 v164, v164, 0, s[72:73]
	v_add_f32_e32 v106, v106, v164
.Lsel_tail_0:
	s_waitcnt lgkmcnt(0)
	s_and_b32 s1, s86, 31
	v_bfe_u32 v184, v184, s1, 1
	v_cmp_eq_u32_e64 s[98:99], 0, v184
	v_mov_b32_e32 v0, s77
	ds_read_b32 v182, v0 offset:16
	s_add_u32 s1, s76, 2
	s_cmp_lt_u32 s1, s79
	s_cbranch_scc0 .Lsel_nost_0
	s_add_u32 s1, s76, 3
	s_cmp_lt_u32 s1, s79
	s_cbranch_scc1 .Lsel_st2_0
	s_waitcnt vmcnt(0)
	s_branch .Lsel_st_0
.Lsel_st2_0:
	s_waitcnt vmcnt(2)
.Lsel_st_0:
	v_add_u32_e32 v0, s83, v101
	ds_write_b128 v0, v[26:29]
	ds_write_b128 v0, v[96:99] offset:9216
	s_branch .Lsel_bar_0
.Lsel_nost_0:
	s_nop 4
	s_mov_b64 s[98:99], -1
.Lsel_bar_0:
	s_waitcnt lgkmcnt(0)
	s_barrier
	s_mov_b64 s[72:73], s[100:101]
	s_mov_b64 s[100:101], s[98:99]
	s_mov_b32 s86, s0
	s_mov_b32 s1, s81
	s_mov_b32 s81, s82
	s_mov_b32 s82, s83
	s_mov_b32 s83, s1
	s_add_u32 s77, s77, 4
	s_add_u32 s76, s76, 1
	s_cmp_lt_u32 s76, s79
	s_cbranch_scc1 .Lsel_step_1
	s_branch .Lsel_exit
.Lsel_step_1:
	s_add_u32 s1, s76, 3
	s_cmp_lt_u32 s1, s79
	s_cbranch_scc0 .Lsel_nogl_1
	v_lshl_add_u32 v0, v182, 6, v100
	v_mad_i64_i32 v[26:27], vcc, v0, s90, v[30:31]
	v_mad_i64_i32 v[96:97], vcc, v0, s90, v[104:105]
	global_load_dwordx4 v[26:29], v[26:27], off
	s_nop 0
	global_load_dwordx4 v[96:99], v[96:97], off
.Lsel_nogl_1:
	v_readfirstlane_b32 s0, v182
	s_lshr_b32 s98, s86, 5
	s_and_b32 s98, s98, 3
	s_lshl_b32 s98, s98, 2
	v_add_u32_e32 v184, s98, v103
	ds_read_b32 v184, v184
	s_cmp_lg_u64 s[100:101], -1
	s_cbranch_scc0 .Lsel_noN_1
	s_cmp_lg_u64 s[72:73], -1
	s_cbranch_scc0 .Lsel_Nonly_1
	v_add_u32_e32 v0, s82, v208
	ds_read_b128 v[108:111], v0
	ds_read_b128 v[112:115], v0 offset:4608
	ds_read_b128 v[116:119], v0 offset:32
	ds_read_b128 v[120:123], v0 offset:4640
	s_add_u32 s1, s76, 1
	s_cmp_lg_u32 s1, s79
	s_cbranch_scc1 .Lsel_nodiag_1b
	v_cndmask_b32_e64 v238, v238, v185, s[6:7]
	v_cndmask_b32_e64 v222, v222, v185, s[8:9]
	v_cndmask_b32_e64 v239, v185, v239, s[10:11]
	v_cndmask_b32_e64 v223, v223, v185, s[12:13]
	v_cndmask_b32_e64 v240, v240, v185, s[14:15]
	v_cndmask_b32_e64 v224, v224, v185, s[16:17]
	v_cndmask_b32_e64 v241, v241, v185, s[18:19]
	v_cndmask_b32_e64 v225, v225, v185, s[20:21]
	v_cndmask_b32_e64 v242, v242, v185, s[22:23]
	v_cndmask_b32_e64 v226, v226, v185, s[24:25]
	v_cndmask_b32_e64 v243, v243, v185, s[26:27]
	v_cndmask_b32_e64 v227, v227, v185, s[28:29]
	v_cndmask_b32_e64 v244, v244, v185, s[30:31]
	v_cndmask_b32_e64 v228, v228, v185, s[34:35]
	v_cndmask_b32_e64 v245, v245, v185, s[36:37]
	v_cndmask_b32_e64 v229, v229, v185, s[38:39]
	v_cndmask_b32_e64 v246, v246, v185, s[40:41]
	v_cndmask_b32_e64 v230, v230, v185, s[42:43]
	v_cndmask_b32_e64 v247, v247, v185, s[44:45]
	v_cndmask_b32_e64 v231, v231, v185, s[46:47]
	v_cndmask_b32_e64 v248, v248, v185, s[48:49]
	v_cndmask_b32_e64 v232, v232, v185, s[50:51]
	v_cndmask_b32_e64 v249, v249, v185, s[52:53]
	v_cndmask_b32_e64 v233, v233, v185, s[54:55]
	v_cndmask_b32_e64 v250, v250, v185, s[56:57]
	v_cndmask_b32_e64 v234, v234, v185, s[58:59]
	v_cndmask_b32_e64 v251, v251, v185, s[60:61]
	v_cndmask_b32_e64 v235, v235, v185, s[62:63]
	v_cndmask_b32_e64 v252, v252, v185, s[64:65]
	v_cndmask_b32_e64 v236, v236, v185, s[66:67]
	v_cndmask_b32_e64 v253, v253, v185, s[68:69]
	v_cndmask_b32_e64 v237, v237, v185, s[70:71]
.Lsel_nodiag_1b:
	v_max3_f32 v107, v238, v239, v240
	v_max3_f32 v160, v222, v223, v224
	v_max3_f32 v107, v107, v241, v242
	v_max3_f32 v160, v160, v225, v226
	v_max3_f32 v107, v107, v243, v244
	v_max3_f32 v160, v160, v227, v228
	v_max3_f32 v107, v107, v245, v246
	v_max3_f32 v160, v160, v229, v230
	v_max3_f32 v107, v107, v247, v248
	v_max3_f32 v160, v160, v231, v232
	v_max3_f32 v107, v107, v249, v250
	v_max3_f32 v160, v160, v233, v234
	v_max_f32_e32 v162, v237, v237
	v_max_f32_e32 v163, v253, v253
	v_max3_f32 v107, v107, v251, v252
	v_max3_f32 v160, v160, v235, v236
	v_max_f32_e32 v162, v163, v162
	v_max3_f32 v107, v107, v160, v162
	v_mov_b32_e32 v160, v107
	s_nop 1
	v_permlane32_swap_b32_e32 v107, v160
	v_max_f32_e32 v160, v160, v160
	v_max_f32_e32 v107, v107, v107
	v_max_f32_e32 v107, v107, v160
	v_cndmask_b32_e64 v107, v107, v185, s[72:73]
	v_cmp_lt_f32_e32 vcc, s91, v107
	s_cbranch_vccz .Lsel_noresc_1b
	s_nop 15
	s_nop 15
	v_max_f32_e32 v107, v107, v107
	v_max_f32_e32 v160, 0, v107
	v_exp_f32_e64 v162, -v160
	v_pk_add_f32 v[238:239], v[238:239], v[160:161] op_sel_hi:[1,0] neg_lo:[0,1] neg_hi:[0,1]
	v_pk_add_f32 v[222:223], v[222:223], v[160:161] op_sel_hi:[1,0] neg_lo:[0,1] neg_hi:[0,1]
	v_pk_add_f32 v[240:241], v[240:241], v[160:161] op_sel_hi:[1,0] neg_lo:[0,1] neg_hi:[0,1]
	v_pk_add_f32 v[224:225], v[224:225], v[160:161] op_sel_hi:[1,0] neg_lo:[0,1] neg_hi:[0,1]
	v_pk_add_f32 v[242:243], v[242:243], v[160:161] op_sel_hi:[1,0] neg_lo:[0,1] neg_hi:[0,1]
	v_pk_add_f32 v[226:227], v[226:227], v[160:161] op_sel_hi:[1,0] neg_lo:[0,1] neg_hi:[0,1]
	v_pk_add_f32 v[244:245], v[244:245], v[160:161] op_sel_hi:[1,0] neg_lo:[0,1] neg_hi:[0,1]
	v_pk_add_f32 v[228:229], v[228:229], v[160:161] op_sel_hi:[1,0] neg_lo:[0,1] neg_hi:[0,1]
	v_pk_add_f32 v[246:247], v[246:247], v[160:161] op_sel_hi:[1,0] neg_lo:[0,1] neg_hi:[0,1]
	v_pk_add_f32 v[230:231], v[230:231], v[160:161] op_sel_hi:[1,0] neg_lo:[0,1] neg_hi:[0,1]
	v_pk_add_f32 v[248:249], v[248:249], v[160:161] op_sel_hi:[1,0] neg_lo:[0,1] neg_hi:[0,1]
	v_pk_add_f32 v[232:233], v[232:233], v[160:161] op_sel_hi:[1,0] neg_lo:[0,1] neg_hi:[0,1]
	v_pk_add_f32 v[250:251], v[250:251], v[160:161] op_sel_hi:[1,0] neg_lo:[0,1] neg_hi:[0,1]
	v_pk_add_f32 v[234:235], v[234:235], v[160:161] op_sel_hi:[1,0] neg_lo:[0,1] neg_hi:[0,1]
	v_pk_add_f32 v[252:253], v[252:253], v[160:161] op_sel_hi:[1,0] neg_lo:[0,1] neg_hi:[0,1]
	v_pk_add_f32 v[236:237], v[236:237], v[160:161] op_sel_hi:[1,0] neg_lo:[0,1] neg_hi:[0,1]
	v_mul_f32_e32 v106, v106, v162
	v_sub_f32_e32 v2, v2, v160
	v_sub_f32_e32 v3, v3, v160
	v_sub_f32_e32 v4, v4, v160
	v_sub_f32_e32 v5, v5, v160
	v_sub_f32_e32 v6, v6, v160
	v_sub_f32_e32 v7, v7, v160
	v_sub_f32_e32 v8, v8, v160
	v_sub_f32_e32 v9, v9, v160
	v_sub_f32_e32 v10, v10, v160
	v_sub_f32_e32 v11, v11, v160
	v_sub_f32_e32 v12, v12, v160
	v_sub_f32_e32 v13, v13, v160
	v_sub_f32_e32 v14, v14, v160
	v_sub_f32_e32 v15, v15, v160
	v_sub_f32_e32 v16, v16, v160
	v_sub_f32_e32 v17, v17, v160
	v_pk_mul_f32 v[48:49], v[48:49], v[162:163] op_sel_hi:[1,0]
	v_pk_mul_f32 v[32:33], v[32:33], v[162:163] op_sel_hi:[1,0]
	v_pk_mul_f32 v[50:51], v[50:51], v[162:163] op_sel_hi:[1,0]
	v_pk_mul_f32 v[34:35], v[34:35], v[162:163] op_sel_hi:[1,0]
	v_pk_mul_f32 v[52:53], v[52:53], v[162:163] op_sel_hi:[1,0]
	v_pk_mul_f32 v[36:37], v[36:37], v[162:163] op_sel_hi:[1,0]
	v_pk_mul_f32 v[54:55], v[54:55], v[162:163] op_sel_hi:[1,0]
	v_pk_mul_f32 v[38:39], v[38:39], v[162:163] op_sel_hi:[1,0]
	v_pk_mul_f32 v[56:57], v[56:57], v[162:163] op_sel_hi:[1,0]
	v_pk_mul_f32 v[40:41], v[40:41], v[162:163] op_sel_hi:[1,0]
	v_pk_mul_f32 v[58:59], v[58:59], v[162:163] op_sel_hi:[1,0]
	v_pk_mul_f32 v[42:43], v[42:43], v[162:163] op_sel_hi:[1,0]
	v_pk_mul_f32 v[60:61], v[60:61], v[162:163] op_sel_hi:[1,0]
	v_pk_mul_f32 v[44:45], v[44:45], v[162:163] op_sel_hi:[1,0]
	v_pk_mul_f32 v[62:63], v[62:63], v[162:163] op_sel_hi:[1,0]
	v_pk_mul_f32 v[46:47], v[46:47], v[162:163] op_sel_hi:[1,0]
	s_nop 1
.Lsel_noresc_1b:
	v_add_u32_e32 v187, s81, v208
	ds_read_b128 v[124:127], v187 offset:9216
	ds_read_b128 v[144:147], v187 offset:13824
	ds_read_b128 v[148:151], v187 offset:9248
	v_exp_f32_e32 v238, v238
	v_exp_f32_e32 v239, v239
	v_exp_f32_e32 v240, v240
	v_exp_f32_e32 v241, v241
	s_waitcnt lgkmcnt(6)
	v_mfma_f32_32x32x16_bf16 v[80:95], v[108:111], v[128:131], v[2:17]
	ds_read_b128 v[108:111], v0 offset:64
	v_exp_f32_e32 v242, v242
	v_exp_f32_e32 v243, v243
	v_exp_f32_e32 v244, v244
	v_exp_f32_e32 v245, v245
	s_waitcnt lgkmcnt(6)
	v_mfma_f32_32x32x16_bf16 v[64:79], v[112:115], v[128:131], v[2:17]
	ds_read_b128 v[112:115], v0 offset:4672
	v_pk_add_f32 v[164:165], v[238:239], 0 op_sel_hi:[1,0]
	v_pk_add_f32 v[164:165], v[240:241], v[164:165]
	v_cvt_pk_bf16_f32 v238, v238, v239
	v_cvt_pk_bf16_f32 v239, v240, v241
	v_pk_add_f32 v[164:165], v[242:243], v[164:165]
	v_pk_add_f32 v[164:165], v[244:245], v[164:165]
	v_cvt_pk_bf16_f32 v240, v242, v243
	v_cvt_pk_bf16_f32 v241, v244, v245
	v_cndmask_b32_e64 v238, v238, 0, s[72:73]
	v_cndmask_b32_e64 v239, v239, 0, s[72:73]
	v_cndmask_b32_e64 v240, v240, 0, s[72:73]
	v_cndmask_b32_e64 v241, v241, 0, s[72:73]
	v_exp_f32_e32 v246, v246
	v_exp_f32_e32 v247, v247
	s_waitcnt lgkmcnt(4)
	v_mfma_f32_32x32x16_bf16 v[48:63], v[124:127], v[238:241], v[48:63]
	ds_read_b128 v[124:127], v187 offset:13856
	v_exp_f32_e32 v248, v248
	v_exp_f32_e32 v249, v249
	s_waitcnt lgkmcnt(4)
	v_mfma_f32_32x32x16_bf16 v[32:47], v[144:147], v[238:241], v[32:47]
	ds_read_b128 v[144:147], v187 offset:9280
	v_exp_f32_e32 v250, v250
	v_exp_f32_e32 v251, v251
	v_mfma_f32_32x32x16_bf16 v[80:95], v[116:119], v[132:135], v[80:95]
	ds_read_b128 v[116:119], v0 offset:96
	v_exp_f32_e32 v252, v252
	v_exp_f32_e32 v253, v253
	v_mfma_f32_32x32x16_bf16 v[64:79], v[120:123], v[132:135], v[64:79]
	ds_read_b128 v[120:123], v0 offset:4704
	v_pk_add_f32 v[164:165], v[246:247], v[164:165]
	v_pk_add_f32 v[164:165], v[248:249], v[164:165]
	v_cvt_pk_bf16_f32 v246, v246, v247
	v_cvt_pk_bf16_f32 v247, v248, v249
	v_pk_add_f32 v[164:165], v[250:251], v[164:165]
	v_pk_add_f32 v[164:165], v[252:253], v[164:165]
	v_cvt_pk_bf16_f32 v248, v250, v251
	v_cvt_pk_bf16_f32 v249, v252, v253
	v_cndmask_b32_e64 v246, v246, 0, s[72:73]
	v_cndmask_b32_e64 v247, v247, 0, s[72:73]
	v_cndmask_b32_e64 v248, v248, 0, s[72:73]
	v_cndmask_b32_e64 v249, v249, 0, s[72:73]
	v_exp_f32_e32 v222, v222
	v_exp_f32_e32 v223, v223
	s_waitcnt lgkmcnt(6)
	v_mfma_f32_32x32x16_bf16 v[48:63], v[148:151], v[246:249], v[48:63]
	ds_read_b128 v[148:151], v187 offset:13888
	v_exp_f32_e32 v224, v224
	v_exp_f32_e32 v225, v225
	s_waitcnt lgkmcnt(4)
	v_mfma_f32_32x32x16_bf16 v[32:47], v[124:127], v[246:249], v[32:47]
	ds_read_b128 v[124:127], v187 offset:9312
	v_exp_f32_e32 v226, v226
	v_exp_f32_e32 v227, v227
	v_mfma_f32_32x32x16_bf16 v[80:95], v[108:111], v[136:139], v[80:95]
	v_exp_f32_e32 v228, v228
	v_exp_f32_e32 v229, v229
	v_mfma_f32_32x32x16_bf16 v[64:79], v[112:115], v[136:139], v[64:79]
	v_pk_add_f32 v[164:165], v[222:223], v[164:165]
	v_pk_add_f32 v[164:165], v[224:225], v[164:165]
	v_cvt_pk_bf16_f32 v222, v222, v223
	v_cvt_pk_bf16_f32 v223, v224, v225
	v_pk_add_f32 v[164:165], v[226:227], v[164:165]
	v_pk_add_f32 v[164:165], v[228:229], v[164:165]
	v_cvt_pk_bf16_f32 v224, v226, v227
	v_cvt_pk_bf16_f32 v225, v228, v229
	v_cndmask_b32_e64 v222, v222, 0, s[72:73]
	v_cndmask_b32_e64 v223, v223, 0, s[72:73]
	v_cndmask_b32_e64 v224, v224, 0, s[72:73]
	v_cndmask_b32_e64 v225, v225, 0, s[72:73]
	v_exp_f32_e32 v230, v230
	v_exp_f32_e32 v231, v231
	s_waitcnt lgkmcnt(4)
	v_mfma_f32_32x32x16_bf16 v[48:63], v[144:147], v[222:225], v[48:63]
	ds_read_b128 v[144:147], v187 offset:13920
	v_exp_f32_e32 v232, v232
	v_exp_f32_e32 v233, v233
	s_waitcnt lgkmcnt(2)
	v_mfma_f32_32x32x16_bf16 v[32:47], v[148:151], v[222:225], v[32:47]
	v_exp_f32_e32 v234, v234
	v_exp_f32_e32 v235, v235
	v_mfma_f32_32x32x16_bf16 v[80:95], v[116:119], v[140:143], v[80:95]
	v_exp_f32_e32 v236, v236
	v_exp_f32_e32 v237, v237
	v_mfma_f32_32x32x16_bf16 v[64:79], v[120:123], v[140:143], v[64:79]
	v_pk_add_f32 v[164:165], v[230:231], v[164:165]
	v_pk_add_f32 v[164:165], v[232:233], v[164:165]
	v_cvt_pk_bf16_f32 v230, v230, v231
	v_cvt_pk_bf16_f32 v231, v232, v233
	v_pk_add_f32 v[164:165], v[234:235], v[164:165]
	v_pk_add_f32 v[164:165], v[236:237], v[164:165]
	v_cvt_pk_bf16_f32 v232, v234, v235
	v_cvt_pk_bf16_f32 v233, v236, v237
	v_cndmask_b32_e64 v230, v230, 0, s[72:73]
	v_cndmask_b32_e64 v231, v231, 0, s[72:73]
	v_cndmask_b32_e64 v232, v232, 0, s[72:73]
	v_cndmask_b32_e64 v233, v233, 0, s[72:73]
	s_nop 1
	s_waitcnt lgkmcnt(1)
	v_mfma_f32_32x32x16_bf16 v[48:63], v[124:127], v[230:233], v[48:63]
	s_waitcnt lgkmcnt(0)
	v_mfma_f32_32x32x16_bf16 v[32:47], v[144:147], v[230:233], v[32:47]
	v_add_f32_e32 v164, v164, v165
	v_cndmask_b32_e64 v164, v164, 0, s[72:73]
	v_add_f32_e32 v106, v106, v164
	s_branch .Lsel_tail_1
.Lsel_Nonly_1:
	v_add_u32_e32 v0, s82, v208
	ds_read_b128 v[108:111], v0
	ds_read_b128 v[112:115], v0 offset:4608
	ds_read_b128 v[116:119], v0 offset:32
	ds_read_b128 v[120:123], v0 offset:4640
	s_waitcnt lgkmcnt(3)
	v_mfma_f32_32x32x16_bf16 v[80:95], v[108:111], v[128:131], v[2:17]
	ds_read_b128 v[108:111], v0 offset:64
	s_waitcnt lgkmcnt(3)
	v_mfma_f32_32x32x16_bf16 v[64:79], v[112:115], v[128:131], v[2:17]
	ds_read_b128 v[112:115], v0 offset:4672
	s_waitcnt lgkmcnt(3)
	v_mfma_f32_32x32x16_bf16 v[80:95], v[116:119], v[132:135], v[80:95]
	ds_read_b128 v[116:119], v0 offset:96
	s_waitcnt lgkmcnt(3)
	v_mfma_f32_32x32x16_bf16 v[64:79], v[120:123], v[132:135], v[64:79]
	ds_read_b128 v[120:123], v0 offset:4704
	s_waitcnt lgkmcnt(3)
	v_mfma_f32_32x32x16_bf16 v[80:95], v[108:111], v[136:139], v[80:95]
	s_waitcnt lgkmcnt(2)
	v_mfma_f32_32x32x16_bf16 v[64:79], v[112:115], v[136:139], v[64:79]
	s_waitcnt lgkmcnt(1)
	v_mfma_f32_32x32x16_bf16 v[80:95], v[116:119], v[140:143], v[80:95]
	s_waitcnt lgkmcnt(0)
	v_mfma_f32_32x32x16_bf16 v[64:79], v[120:123], v[140:143], v[64:79]
	s_branch .Lsel_tail_1
.Lsel_noN_1:
	s_cmp_lg_u64 s[72:73], -1
	s_cbranch_scc0 .Lsel_tail_1
	s_add_u32 s1, s76, 1
	s_cmp_lg_u32 s1, s79
	s_cbranch_scc1 .Lsel_nodiag_1c
	v_cndmask_b32_e64 v238, v238, v185, s[6:7]
	v_cndmask_b32_e64 v222, v222, v185, s[8:9]
	v_cndmask_b32_e64 v239, v185, v239, s[10:11]
	v_cndmask_b32_e64 v223, v223, v185, s[12:13]
	v_cndmask_b32_e64 v240, v240, v185, s[14:15]
	v_cndmask_b32_e64 v224, v224, v185, s[16:17]
	v_cndmask_b32_e64 v241, v241, v185, s[18:19]
	v_cndmask_b32_e64 v225, v225, v185, s[20:21]
	v_cndmask_b32_e64 v242, v242, v185, s[22:23]
	v_cndmask_b32_e64 v226, v226, v185, s[24:25]
	v_cndmask_b32_e64 v243, v243, v185, s[26:27]
	v_cndmask_b32_e64 v227, v227, v185, s[28:29]
	v_cndmask_b32_e64 v244, v244, v185, s[30:31]
	v_cndmask_b32_e64 v228, v228, v185, s[34:35]
	v_cndmask_b32_e64 v245, v245, v185, s[36:37]
	v_cndmask_b32_e64 v229, v229, v185, s[38:39]
	v_cndmask_b32_e64 v246, v246, v185, s[40:41]
	v_cndmask_b32_e64 v230, v230, v185, s[42:43]
	v_cndmask_b32_e64 v247, v247, v185, s[44:45]
	v_cndmask_b32_e64 v231, v231, v185, s[46:47]
	v_cndmask_b32_e64 v248, v248, v185, s[48:49]
	v_cndmask_b32_e64 v232, v232, v185, s[50:51]
	v_cndmask_b32_e64 v249, v249, v185, s[52:53]
	v_cndmask_b32_e64 v233, v233, v185, s[54:55]
	v_cndmask_b32_e64 v250, v250, v185, s[56:57]
	v_cndmask_b32_e64 v234, v234, v185, s[58:59]
	v_cndmask_b32_e64 v251, v251, v185, s[60:61]
	v_cndmask_b32_e64 v235, v235, v185, s[62:63]
	v_cndmask_b32_e64 v252, v252, v185, s[64:65]
	v_cndmask_b32_e64 v236, v236, v185, s[66:67]
	v_cndmask_b32_e64 v253, v253, v185, s[68:69]
	v_cndmask_b32_e64 v237, v237, v185, s[70:71]

.Lsel_noresc_1c:
	v_add_u32_e32 v187, s81, v208
	ds_read_b128 v[124:127], v187 offset:9216
	ds_read_b128 v[144:147], v187 offset:13824
	ds_read_b128 v[148:151], v187 offset:9248
	v_exp_f32_e32 v238, v238
	v_exp_f32_e32 v239, v239
	v_exp_f32_e32 v240, v240
	v_exp_f32_e32 v241, v241
	v_exp_f32_e32 v242, v242
	v_exp_f32_e32 v243, v243
	v_exp_f32_e32 v244, v244
	v_exp_f32_e32 v245, v245
	v_pk_add_f32 v[164:165], v[238:239], 0 op_sel_hi:[1,0]
	v_pk_add_f32 v[164:165], v[240:241], v[164:165]
	v_cvt_pk_bf16_f32 v238, v238, v239
	v_cvt_pk_bf16_f32 v239, v240, v241
	v_pk_add_f32 v[164:165], v[242:243], v[164:165]
	v_pk_add_f32 v[164:165], v[244:245], v[164:165]
	v_cvt_pk_bf16_f32 v240, v242, v243
	v_cvt_pk_bf16_f32 v241, v244, v245
	v_cndmask_b32_e64 v238, v238, 0, s[72:73]
	v_cndmask_b32_e64 v239, v239, 0, s[72:73]
	v_cndmask_b32_e64 v240, v240, 0, s[72:73]
	v_cndmask_b32_e64 v241, v241, 0, s[72:73]
	v_exp_f32_e32 v246, v246
	v_exp_f32_e32 v247, v247
	s_waitcnt lgkmcnt(2)
	v_mfma_f32_32x32x16_bf16 v[48:63], v[124:127], v[238:241], v[48:63]
	ds_read_b128 v[124:127], v187 offset:13856
	v_exp_f32_e32 v248, v248
	v_exp_f32_e32 v249, v249
	s_waitcnt lgkmcnt(2)
	v_mfma_f32_32x32x16_bf16 v[32:47], v[144:147], v[238:241], v[32:47]
	ds_read_b128 v[144:147], v187 offset:9280
	v_exp_f32_e32 v250, v250
	v_exp_f32_e32 v251, v251
	v_exp_f32_e32 v252, v252
	v_exp_f32_e32 v253, v253
	v_pk_add_f32 v[164:165], v[246:247], v[164:165]
	v_pk_add_f32 v[164:165], v[248:249], v[164:165]
	v_cvt_pk_bf16_f32 v246, v246, v247
	v_cvt_pk_bf16_f32 v247, v248, v249
	v_pk_add_f32 v[164:165], v[250:251], v[164:165]
	v_pk_add_f32 v[164:165], v[252:253], v[164:165]
	v_cvt_pk_bf16_f32 v248, v250, v251
	v_cvt_pk_bf16_f32 v249, v252, v253
	v_cndmask_b32_e64 v246, v246, 0, s[72:73]
	v_cndmask_b32_e64 v247, v247, 0, s[72:73]
	v_cndmask_b32_e64 v248, v248, 0, s[72:73]
	v_cndmask_b32_e64 v249, v249, 0, s[72:73]
	v_exp_f32_e32 v222, v222
	v_exp_f32_e32 v223, v223
	s_waitcnt lgkmcnt(2)
	v_mfma_f32_32x32x16_bf16 v[48:63], v[148:151], v[246:249], v[48:63]
	ds_read_b128 v[148:151], v187 offset:13888
	v_exp_f32_e32 v224, v224
	v_exp_f32_e32 v225, v225
	s_waitcnt lgkmcnt(2)
	v_mfma_f32_32x32x16_bf16 v[32:47], v[124:127], v[246:249], v[32:47]
	ds_read_b128 v[124:127], v187 offset:9312
	v_exp_f32_e32 v226, v226
	v_exp_f32_e32 v227, v227
	v_exp_f32_e32 v228, v228
	v_exp_f32_e32 v229, v229
	v_pk_add_f32 v[164:165], v[222:223], v[164:165]
	v_pk_add_f32 v[164:165], v[224:225], v[164:165]
	v_cvt_pk_bf16_f32 v222, v222, v223
	v_cvt_pk_bf16_f32 v223, v224, v225
	v_pk_add_f32 v[164:165], v[226:227], v[164:165]
	v_pk_add_f32 v[164:165], v[228:229], v[164:165]
	v_cvt_pk_bf16_f32 v224, v226, v227
	v_cvt_pk_bf16_f32 v225, v228, v229
	v_cndmask_b32_e64 v222, v222, 0, s[72:73]
	v_cndmask_b32_e64 v223, v223, 0, s[72:73]
	v_cndmask_b32_e64 v224, v224, 0, s[72:73]
	v_cndmask_b32_e64 v225, v225, 0, s[72:73]
	v_exp_f32_e32 v230, v230
	v_exp_f32_e32 v231, v231
	s_waitcnt lgkmcnt(2)
	v_mfma_f32_32x32x16_bf16 v[48:63], v[144:147], v[222:225], v[48:63]
	ds_read_b128 v[144:147], v187 offset:13920
	v_exp_f32_e32 v232, v232
	v_exp_f32_e32 v233, v233
	s_waitcnt lgkmcnt(2)
	v_mfma_f32_32x32x16_bf16 v[32:47], v[148:151], v[222:225], v[32:47]
	v_exp_f32_e32 v234, v234
	v_exp_f32_e32 v235, v235
	v_exp_f32_e32 v236, v236
	v_exp_f32_e32 v237, v237
	v_pk_add_f32 v[164:165], v[230:231], v[164:165]
	v_pk_add_f32 v[164:165], v[232:233], v[164:165]
	v_cvt_pk_bf16_f32 v230, v230, v231
	v_cvt_pk_bf16_f32 v231, v232, v233
	v_pk_add_f32 v[164:165], v[234:235], v[164:165]
	v_pk_add_f32 v[164:165], v[236:237], v[164:165]
	v_cvt_pk_bf16_f32 v232, v234, v235
	v_cvt_pk_bf16_f32 v233, v236, v237
	v_cndmask_b32_e64 v230, v230, 0, s[72:73]
	v_cndmask_b32_e64 v231, v231, 0, s[72:73]
	v_cndmask_b32_e64 v232, v232, 0, s[72:73]
	v_cndmask_b32_e64 v233, v233, 0, s[72:73]
	s_nop 1
	s_waitcnt lgkmcnt(1)
	v_mfma_f32_32x32x16_bf16 v[48:63], v[124:127], v[230:233], v[48:63]
	s_waitcnt lgkmcnt(0)
	v_mfma_f32_32x32x16_bf16 v[32:47], v[144:147], v[230:233], v[32:47]
	v_add_f32_e32 v164, v164, v165
	v_cndmask_b32_e64 v164, v164, 0, s[72:73]
	v_add_f32_e32 v106, v106, v164

.Lsel_st_1:
	v_add_u32_e32 v0, s83, v101
	ds_write_b128 v0, v[18:21]
	ds_write_b128 v0, v[22:25] offset:9216
	s_branch .Lsel_bar_1

.Lsel_exit:
	s_nop 15
	v_mov_b32_e32 v107, v106
	s_nop 1
	v_permlane32_swap_b32_e32 v106, v107
	v_add_f32_e32 v106, v106, v107
	v_mov_b32_e32 v160, 0x3f317218
	v_mov_b32_e32 v182, 0x358637bd
	v_mov_b32_e32 v184, 0x3e38aa3b
	v_mov_b32_e32 v187, 0x2640
	s_branch .LBB0_946

	.amdhsa_kernel _Z10hybrid_fwd6Params
		.amdhsa_group_segment_fixed_size 0
		.amdhsa_private_segment_fixed_size 0
		.amdhsa_kernarg_size 400
		.amdhsa_user_sgpr_count 2
		.amdhsa_user_sgpr_dispatch_ptr 0
		.amdhsa_user_sgpr_queue_ptr 0
		.amdhsa_user_sgpr_kernarg_segment_ptr 1
		.amdhsa_user_sgpr_dispatch_id 0
		.amdhsa_user_sgpr_kernarg_preload_length 0
		.amdhsa_user_sgpr_kernarg_preload_offset 0
		.amdhsa_user_sgpr_private_segment_size 0
		.amdhsa_uses_dynamic_stack 0
		.amdhsa_enable_private_segment 0
		.amdhsa_system_sgpr_workgroup_id_x 1
		.amdhsa_system_sgpr_workgroup_id_y 0
		.amdhsa_system_sgpr_workgroup_id_z 0
		.amdhsa_system_sgpr_workgroup_info 0
		.amdhsa_system_vgpr_workitem_id 2
		.amdhsa_next_free_vgpr 256
		.amdhsa_next_free_sgpr 102
		.amdhsa_accum_offset 256
		.amdhsa_reserve_vcc 1
		.amdhsa_float_round_mode_32 0
		.amdhsa_float_round_mode_16_64 0
		.amdhsa_float_denorm_mode_32 3
		.amdhsa_float_denorm_mode_16_64 3
		.amdhsa_dx10_clamp 1
		.amdhsa_ieee_mode 1
		.amdhsa_fp16_overflow 0
		.amdhsa_tg_split 0
		.amdhsa_exception_fp_ieee_invalid_op 0
		.amdhsa_exception_fp_denorm_src 0
		.amdhsa_exception_fp_ieee_div_zero 0
		.amdhsa_exception_fp_ieee_overflow 0
		.amdhsa_exception_fp_ieee_underflow 0
		.amdhsa_exception_fp_ieee_inexact 0
		.amdhsa_exception_int_div_zero 0
	.end_amdhsa_kernel

amdhsa.kernels:
  - .agpr_count:     0
    .args:
      - .offset:         0
        .size:           144
        .value_kind:     by_value
      - .offset:         144
        .size:           4
        .value_kind:     hidden_block_count_x
      - .offset:         148
        .size:           4
        .value_kind:     hidden_block_count_y
      - .offset:         152
        .size:           4
        .value_kind:     hidden_block_count_z
      - .offset:         156
        .size:           2
        .value_kind:     hidden_group_size_x
      - .offset:         158
        .size:           2
        .value_kind:     hidden_group_size_y
      - .offset:         160
        .size:           2
        .value_kind:     hidden_group_size_z
      - .offset:         162
        .size:           2
        .value_kind:     hidden_remainder_x
      - .offset:         164
        .size:           2
        .value_kind:     hidden_remainder_y
      - .offset:         166
        .size:           2
        .value_kind:     hidden_remainder_z
      - .offset:         184
        .size:           8
        .value_kind:     hidden_global_offset_x
      - .offset:         192
        .size:           8
        .value_kind:     hidden_global_offset_y
      - .offset:         200
        .size:           8
        .value_kind:     hidden_global_offset_z
      - .offset:         208
        .size:           2
        .value_kind:     hidden_grid_dims
      - .offset:         232
        .size:           8
        .value_kind:     hidden_multigrid_sync_arg
      - .offset:         264
        .size:           4
        .value_kind:     hidden_dynamic_lds_size
    .group_segment_fixed_size: 0
    .kernarg_segment_align: 8
    .kernarg_segment_size: 400
    .language:       OpenCL C
    .language_version:
      - 2
      - 0
    .max_flat_workgroup_size: 512
    .name:           _Z10hybrid_fwd6Params
    .private_segment_fixed_size: 0
    .sgpr_count:     108
    .sgpr_spill_count: 92
    .symbol:         _Z10hybrid_fwd6Params.kd
    .uniform_work_group_size: 1
    .uses_dynamic_stack: false
    .vgpr_count:     256
    .vgpr_spill_count: 0
    .wavefront_size: 64
